# phase 0 row loop: next iteration's two rows prefetched into registers, loop-top wait counted (6 stores follow the prefetch loads)
# baseline (speedup 1.0000x reference)
; #define LAS __attribute__((address_space(3)))
; __device__ __forceinline__ void stage_wig(CArgs& A, Frame& F, int L) {
;     const float* w_in = A.in[9] + (size_t)L * D * DIN; LAS float* wig = (LAS float*)(F.lds + WIG_OFF);
;     float t[16];
; #pragma unroll
;     for (int q = 0; q < 16; ++q) { const int i = F.tid + NT * q; t[q] = w_in[(size_t)(i >> 3) * DIN + 3072 + (i & 7)]; }
; #pragma unroll
;     for (int q = 0; q < 16; ++q) { const int i = F.tid + NT * q; wig[(i & 7) * 1024 + (i >> 3)] = t[q]; }
; }
; __global__ void __launch_bounds__(NT, 2) fwd(const Args args) {
;     ...
;         stage_wig(A, F, 0); __syncthreads();
.LBB0_7:
	s_lshr_b32 s0, s4, 6
	v_writelane_b32 v253, s0, 11
	s_lshl_b32 s96, s94, 3
	v_readlane_b32 s0, v253, 1
	v_readlane_b32 s2, v253, 3
	v_readlane_b32 s1, v253, 2
	v_readlane_b32 s3, v253, 4
	s_cmp_lt_i32 s2, 1
	s_cselect_b64 s[0:1], -1, 0
	s_cmp_gt_i32 s3, 0
	s_cselect_b64 s[2:3], -1, 0
	s_and_b64 s[0:1], s[0:1], s[2:3]
	s_andn2_b64 vcc, exec, s[0:1]
	s_cbranch_vccnz .LBB0_45
	v_readlane_b32 s20, v253, 5
	v_readlane_b32 s21, v253, 6
	s_mov_b32 s2, 0
	s_mov_b32 s4, 0
	s_load_dwordx2 s[2:3], s[20:21], 0xe8
	v_readlane_b32 s23, v253, 11
	v_mbcnt_lo_u32_b32 v1, -1, s4
	v_readlane_b32 s4, v253, 0
	v_mbcnt_hi_u32_b32 v38, -1, v1
	s_mov_b32 s22, s4
	s_load_dwordx2 s[24:25], s[20:21], 0x48
	v_lshl_add_u32 v34, s23, 6, v38
	v_and_b32_e32 v1, 7, v38
	v_ashrrev_i32_e32 v20, 3, v34
	s_movk_i32 s6, 0x6820
	s_waitcnt lgkmcnt(0)
	v_mov_b64_e32 v[2:3], s[24:25]
	v_mad_i64_i32 v[4:5], s[4:5], v20, s6, v[2:3]
	v_lshlrev_b32_e32 v36, 2, v1
	v_mov_b32_e32 v37, 0
	v_add_u32_e32 v6, 0x200, v34
	v_lshl_add_u64 v[4:5], v[4:5], 0, v[36:37]
	s_movk_i32 s7, 0x3000
	v_ashrrev_i32_e32 v21, 3, v6
	v_add_co_u32_e32 v4, vcc, s7, v4
	v_mad_i64_i32 v[6:7], s[4:5], v21, s6, v[2:3]
	v_add_u32_e32 v8, 0x400, v34
	v_addc_co_u32_e32 v5, vcc, 0, v5, vcc
	v_lshl_add_u64 v[6:7], v[6:7], 0, v[36:37]
	v_ashrrev_i32_e32 v22, 3, v8
	v_add_co_u32_e32 v6, vcc, s7, v6
	v_mad_i64_i32 v[8:9], s[4:5], v22, s6, v[2:3]
	v_add_u32_e32 v10, 0x600, v34
	v_addc_co_u32_e32 v7, vcc, 0, v7, vcc
	v_lshl_add_u64 v[8:9], v[8:9], 0, v[36:37]
	v_ashrrev_i32_e32 v23, 3, v10
	v_add_co_u32_e32 v8, vcc, s7, v8
	v_mad_i64_i32 v[10:11], s[4:5], v23, s6, v[2:3]
	v_add_u32_e32 v12, 0x800, v34
	v_addc_co_u32_e32 v9, vcc, 0, v9, vcc
	v_lshl_add_u64 v[10:11], v[10:11], 0, v[36:37]
	v_ashrrev_i32_e32 v24, 3, v12
	v_add_co_u32_e32 v10, vcc, s7, v10
	v_mad_i64_i32 v[12:13], s[4:5], v24, s6, v[2:3]
	v_add_u32_e32 v14, 0xa00, v34
	v_addc_co_u32_e32 v11, vcc, 0, v11, vcc
	v_lshl_add_u64 v[12:13], v[12:13], 0, v[36:37]
	v_ashrrev_i32_e32 v25, 3, v14
	v_add_co_u32_e32 v12, vcc, s7, v12
	v_mad_i64_i32 v[14:15], s[4:5], v25, s6, v[2:3]
	v_add_u32_e32 v16, 0xc00, v34
	v_addc_co_u32_e32 v13, vcc, 0, v13, vcc
	v_lshl_add_u64 v[14:15], v[14:15], 0, v[36:37]
	v_ashrrev_i32_e32 v26, 3, v16
	v_add_co_u32_e32 v14, vcc, s7, v14
	v_mad_i64_i32 v[16:17], s[4:5], v26, s6, v[2:3]
	v_add_u32_e32 v18, 0xe00, v34
	v_addc_co_u32_e32 v15, vcc, 0, v15, vcc
	v_lshl_add_u64 v[16:17], v[16:17], 0, v[36:37]
	v_ashrrev_i32_e32 v27, 3, v18
	v_add_co_u32_e32 v16, vcc, s7, v16
	v_mad_i64_i32 v[18:19], s[4:5], v27, s6, v[2:3]
	s_nop 0
	v_addc_co_u32_e32 v17, vcc, 0, v17, vcc
	v_lshl_add_u64 v[18:19], v[18:19], 0, v[36:37]
	v_add_co_u32_e32 v18, vcc, s7, v18
	s_nop 1
	v_addc_co_u32_e32 v19, vcc, 0, v19, vcc
	global_load_dword v28, v[4:5], off
	global_load_dword v29, v[6:7], off
	global_load_dword v30, v[8:9], off
	global_load_dword v31, v[10:11], off
	global_load_dword v32, v[12:13], off
	global_load_dword v33, v[14:15], off
	global_load_dword v35, v[16:17], off
	global_load_dword v39, v[18:19], off
	v_add_u32_e32 v4, 0x1000, v34
	v_ashrrev_i32_e32 v16, 3, v4
	v_mad_i64_i32 v[4:5], s[4:5], v16, s6, v[2:3]
	v_lshl_add_u64 v[4:5], v[4:5], 0, v[36:37]
	v_add_co_u32_e32 v4, vcc, s7, v4
	v_add_u32_e32 v6, 0x1400, v34
	s_nop 0
	v_addc_co_u32_e32 v5, vcc, 0, v5, vcc
	global_load_dword v17, v[4:5], off
	v_add_u32_e32 v4, 0x1200, v34
	v_ashrrev_i32_e32 v18, 3, v4
	v_mad_i64_i32 v[4:5], s[4:5], v18, s6, v[2:3]
	v_lshl_add_u64 v[4:5], v[4:5], 0, v[36:37]
	v_ashrrev_i32_e32 v19, 3, v6
	v_add_co_u32_e32 v4, vcc, s7, v4
	v_mad_i64_i32 v[6:7], s[4:5], v19, s6, v[2:3]
	v_add_u32_e32 v8, 0x1600, v34
	v_addc_co_u32_e32 v5, vcc, 0, v5, vcc
	v_lshl_add_u64 v[6:7], v[6:7], 0, v[36:37]
	v_ashrrev_i32_e32 v40, 3, v8
	v_add_co_u32_e32 v6, vcc, s7, v6
	v_mad_i64_i32 v[8:9], s[4:5], v40, s6, v[2:3]
	v_add_u32_e32 v10, 0x1800, v34
	v_addc_co_u32_e32 v7, vcc, 0, v7, vcc
	v_lshl_add_u64 v[8:9], v[8:9], 0, v[36:37]
	v_ashrrev_i32_e32 v41, 3, v10
	v_add_co_u32_e32 v8, vcc, s7, v8
	v_mad_i64_i32 v[10:11], s[4:5], v41, s6, v[2:3]
	v_add_u32_e32 v12, 0x1a00, v34
	v_addc_co_u32_e32 v9, vcc, 0, v9, vcc
	v_lshl_add_u64 v[10:11], v[10:11], 0, v[36:37]
	v_ashrrev_i32_e32 v42, 3, v12
	v_add_co_u32_e32 v10, vcc, s7, v10
	v_mad_i64_i32 v[12:13], s[4:5], v42, s6, v[2:3]
	v_add_u32_e32 v14, 0x1c00, v34
	v_addc_co_u32_e32 v11, vcc, 0, v11, vcc
	v_lshl_add_u64 v[12:13], v[12:13], 0, v[36:37]
	v_ashrrev_i32_e32 v43, 3, v14
	v_add_co_u32_e32 v12, vcc, s7, v12
	v_mad_i64_i32 v[14:15], s[4:5], v43, s6, v[2:3]
	s_nop 0
	v_addc_co_u32_e32 v13, vcc, 0, v13, vcc
	v_lshl_add_u64 v[14:15], v[14:15], 0, v[36:37]
	v_add_co_u32_e32 v14, vcc, s7, v14
	s_nop 1
	v_addc_co_u32_e32 v15, vcc, 0, v15, vcc
	global_load_dword v44, v[4:5], off
	global_load_dword v45, v[6:7], off
	global_load_dword v46, v[8:9], off
	global_load_dword v47, v[10:11], off
	global_load_dword v48, v[12:13], off
	global_load_dword v49, v[14:15], off
	v_add_u32_e32 v4, 0x1e00, v34
	v_ashrrev_i32_e32 v4, 3, v4
	v_mad_i64_i32 v[2:3], s[4:5], v4, s6, v[2:3]
	v_lshl_add_u64 v[2:3], v[2:3], 0, v[36:37]
	v_add_co_u32_e32 v2, vcc, s7, v2
	s_lshl_b32 s4, s22, 3
	s_nop 0
	v_addc_co_u32_e32 v3, vcc, 0, v3, vcc
	global_load_dword v2, v[2:3], off
	v_lshlrev_b32_e32 v3, 12, v38
	s_add_i32 s26, s4, s23
	s_add_i32 s4, 0, 0x12000
	v_and_b32_e32 v3, 0x7000, v3
	v_add_u32_e32 v3, s4, v3
	v_lshl_add_u32 v5, v20, 2, v3
	s_waitcnt vmcnt(15)
	ds_write_b32 v5, v28
	v_lshl_add_u32 v5, v21, 2, v3
	s_waitcnt vmcnt(14)
	ds_write_b32 v5, v29
	v_lshl_add_u32 v5, v22, 2, v3
	s_waitcnt vmcnt(13)
	ds_write_b32 v5, v30
	v_lshl_add_u32 v5, v23, 2, v3
	s_waitcnt vmcnt(12)
	ds_write_b32 v5, v31
	v_lshl_add_u32 v5, v24, 2, v3
	s_waitcnt vmcnt(11)
	ds_write_b32 v5, v32
	v_lshl_add_u32 v5, v25, 2, v3
	s_waitcnt vmcnt(10)
	ds_write_b32 v5, v33
	v_lshl_add_u32 v5, v26, 2, v3
	s_waitcnt vmcnt(9)
	ds_write_b32 v5, v35
	v_lshl_add_u32 v5, v27, 2, v3
	s_waitcnt vmcnt(8)
	ds_write_b32 v5, v39
	v_lshl_add_u32 v5, v16, 2, v3
	s_waitcnt vmcnt(7)
	ds_write_b32 v5, v17
	v_lshl_add_u32 v5, v18, 2, v3
	s_abs_i32 s4, s96
	v_cvt_f32_u32_e32 v6, s4
	s_sub_i32 s6, 0, s4
	s_ashr_i32 s5, s96, 31
	s_waitcnt vmcnt(6)
	ds_write_b32 v5, v44
	v_lshl_add_u32 v5, v19, 2, v3
	s_waitcnt vmcnt(5)
	ds_write_b32 v5, v45
	v_lshl_add_u32 v5, v40, 2, v3
	s_waitcnt vmcnt(4)
	ds_write_b32 v5, v46
	v_lshl_add_u32 v5, v41, 2, v3
	s_waitcnt vmcnt(3)
	ds_write_b32 v5, v47
	v_lshl_add_u32 v5, v42, 2, v3
	s_waitcnt vmcnt(2)
	ds_write_b32 v5, v48
	v_lshl_add_u32 v5, v43, 2, v3
	s_waitcnt vmcnt(1)
	ds_write_b32 v5, v49
	v_rcp_iflag_f32_e32 v5, v6
	v_lshl_add_u32 v3, v4, 2, v3
	s_waitcnt vmcnt(0)
	ds_write_b32 v3, v2
	v_mul_f32_e32 v2, 0x4f7ffffe, v5
	v_cvt_u32_f32_e32 v2, v2
	s_waitcnt lgkmcnt(0)
	s_barrier
; __global__ void __launch_bounds__(NT, 2) fwd(const Args args) {
;     ...
;         { int m0, m1; row_range(F, m0, m1);
;           for (int m = m0; m < m1; m += 2) { const int mb = (m + 1 < m1) ? m + 1 : m; f32x4 va[4], vb[4];
;               row_load(m < TP ? A.in[0] + (size_t)m * D : A.in[1] + (size_t)(m - TP) * D, F.lane, va); row_load(mb < TP ? A.in[0] + (size_t)mb * D : A.in[1] + (size_t)(mb - TP) * D, F.lane, vb);
	v_readfirstlane_b32 s7, v2
	s_mul_i32 s6, s6, s7
	s_mul_hi_u32 s6, s7, s6
	s_add_i32 s7, s7, s6
	s_mul_hi_u32 s6, s7, 0x4200
	s_mul_i32 s7, s6, s4
	s_sub_i32 s7, 0x4200, s7
	s_sub_i32 s8, s7, s4
	s_add_i32 s9, s6, 1
	s_cmp_ge_u32 s7, s4
	s_cselect_b32 s7, s8, s7
	s_cselect_b32 s6, s9, s6
	s_sub_i32 s8, s7, s4
	s_add_i32 s9, s6, 1
	s_cmp_ge_u32 s7, s4
	s_cselect_b32 s4, s9, s6
	s_cselect_b32 s28, s8, s7
	s_xor_b32 s4, s4, s5
	s_sub_i32 s7, s4, s5
	s_min_i32 s6, s26, s28
	s_mul_i32 s30, s7, s26
	s_add_i32 s6, s30, s6
	s_cmp_lt_i32 s26, s28
	s_cselect_b64 s[4:5], -1, 0
	s_cmp_lg_u64 s[4:5], 0
	s_addc_u32 s38, s6, s7
	s_cmp_ge_i32 s6, s38
	s_cbranch_scc1 .LBB0_15
	v_lshlrev_b32_e32 v2, 3, v38
	s_load_dwordx2 s[18:19], s[20:21], 0x50
	v_ashrrev_i32_e32 v3, 31, v2
	v_lshlrev_b64 v[4:5], 1, v[2:3]
	v_lshl_add_u64 v[6:7], s[2:3], 0, v[4:5]
	s_mov_b64 s[34:35], 0x7680000
	v_ashrrev_i32_e32 v39, 31, v38
	v_lshl_add_u64 v[40:41], v[6:7], 0, s[34:35]
	v_lshlrev_b64 v[6:7], 2, v[38:39]
	s_waitcnt lgkmcnt(0)
	v_lshl_add_u64 v[8:9], s[18:19], 0, v[6:7]
	s_mov_b64 s[18:19], 0x3000
	v_lshl_add_u64 v[42:43], v[8:9], 0, s[18:19]
	global_load_dword v149, v[42:43], off
	v_lshl_add_u64 v[8:9], s[2:3], 0, v[6:7]
	s_mov_b64 s[36:37], 0x1b000000
	s_ashr_i32 s27, s26, 31
	v_lshl_add_u64 v[44:45], v[8:9], 0, s[36:37]
	s_ashr_i32 s29, s28, 31
	v_mov_b64_e32 v[8:9], s[26:27]
	v_cmp_lt_i64_e64 s[18:19], s[28:29], v[8:9]
	s_and_b64 s[18:19], s[18:19], exec
	s_cselect_b32 s19, s29, s27
	s_cselect_b32 s18, s28, s26
	s_ashr_i32 s27, s30, 31
	s_add_u32 s18, s18, s30
	s_addc_u32 s19, s19, s27
	s_lshl_b64 s[28:29], s[18:19], 11
	s_add_u32 s28, s2, s28
	s_addc_u32 s29, s3, s29
	v_lshl_add_u64 v[4:5], s[28:29], 0, v[4:5]
	s_lshl_b64 s[28:29], s[18:19], 5
	s_add_u32 s28, s2, s28
	s_addc_u32 s29, s3, s29
	v_lshlrev_b32_e32 v10, 5, v38
	v_lshl_add_u64 v[46:47], v[4:5], 0, s[34:35]
	v_lshl_add_u64 v[4:5], s[28:29], 0, v[6:7]
	v_cmp_gt_i32_e32 vcc, 8, v38
	v_cmp_eq_u32_e64 s[16:17], 1, v38
	v_cmp_eq_u32_e64 s[4:5], 2, v38
	v_cmp_eq_u32_e64 s[6:7], 3, v38
	v_cmp_eq_u32_e64 s[8:9], 4, v38
	v_cmp_eq_u32_e64 s[10:11], 5, v38
	v_cmp_eq_u32_e64 s[12:13], 6, v38
	v_cmp_eq_u32_e64 s[14:15], 7, v38
	v_lshl_add_u64 v[48:49], v[4:5], 0, s[36:37]
	s_mov_b64 s[28:29], 0
	v_lshlrev_b64 v[50:51], 2, v[2:3]
	s_mov_b64 s[30:31], 0x1000
	v_add_u32_e32 v35, 0, v10
	s_add_i32 s41, s38, -1
	s_add_u32 s27, s18, s28
	s_add_i32 s27, s27, 0
	s_add_i32 s41, s38, -1
	s_min_i32 s27, s27, s41
	s_add_i32 s36, s27, 0xffffc000
	s_cmpk_lt_i32 s27, 0x4000
	s_cselect_b32 s36, s27, s36
	s_cselect_b32 s27, 0, 8
	s_mov_b32 s37, 0
	s_add_u32 s40, s20, s27
	s_addc_u32 s41, s21, 0
	s_load_dwordx2 s[40:41], s[40:41], 0x0
	s_lshl_b64 s[36:37], s[36:37], 12
	s_waitcnt lgkmcnt(0)
	s_add_u32 s36, s40, s36
	s_addc_u32 s37, s41, s37
	v_lshl_add_u64 v[182:183], s[36:37], 0, v[50:51]
	global_load_dwordx4 v[150:153], v[182:183], off
	global_load_dwordx4 v[154:157], v[182:183], off offset:16
	global_load_dwordx4 v[158:161], v[182:183], off offset:2048
	global_load_dwordx4 v[162:165], v[182:183], off offset:2064
	s_add_u32 s27, s18, s28
	s_add_i32 s27, s27, 1
	s_add_i32 s41, s38, -1
	s_min_i32 s27, s27, s41
	s_add_i32 s36, s27, 0xffffc000
	s_cmpk_lt_i32 s27, 0x4000
	s_cselect_b32 s36, s27, s36
	s_cselect_b32 s27, 0, 8
	s_mov_b32 s37, 0
	s_add_u32 s40, s20, s27
	s_addc_u32 s41, s21, 0
	s_load_dwordx2 s[40:41], s[40:41], 0x0
	s_lshl_b64 s[36:37], s[36:37], 12
	s_waitcnt lgkmcnt(0)
	s_add_u32 s36, s40, s36
	s_addc_u32 s37, s41, s37
	v_lshl_add_u64 v[182:183], s[36:37], 0, v[50:51]
	global_load_dwordx4 v[166:169], v[182:183], off
	global_load_dwordx4 v[170:173], v[182:183], off offset:16
	global_load_dwordx4 v[174:177], v[182:183], off offset:2048
	global_load_dwordx4 v[178:181], v[182:183], off offset:2064
	s_waitcnt vmcnt(0)
	s_branch .LBB0_11

; #define LAS __attribute__((address_space(3)))
; __device__ __forceinline__ float wave_sum(float v) { return rdlane(dpp_sum63(v), 63); }
; __device__ __forceinline__ void row_finalize(CArgs& A, Frame& F, int m, const f32x4 (&v)[4], int Ln) {
;     row_store_bf(WSP(bf16, WS_X) + (size_t)m * D, F.lane, v);
;     const LAS float* wig = (const LAS float*)(F.lds + WIG_OFF); const float* b_in = A.in[10] + (size_t)Ln * DIN + 3072;
;     float r[8];
; #pragma unroll
;     for (int c = 0; c < 8; ++c) { float s = 0.f;
; #pragma unroll
;         for (int j = 0; j < 4; ++j) { const f32x4 w = *(const LAS f32x4*)(wig + c * 1024 + RCOL(F.lane, j)); s += (v[j][0] * w[0] + v[j][1] * w[1]) + (v[j][2] * w[2] + v[j][3] * w[3]); }
;         r[c] = wave_sum(s); if (c & 1) asm volatile("" ::: "memory"); }
; __global__ void __launch_bounds__(NT, 2) fwd(const Args args) {
;     ...
;           for (int m = m0; m < m1; m += 2) { const int mb = (m + 1 < m1) ? m + 1 : m; f32x4 va[4], vb[4];
;               row_load(m < TP ? A.in[0] + (size_t)m * D : A.in[1] + (size_t)(m - TP) * D, F.lane, va); row_load(mb < TP ? A.in[0] + (size_t)mb * D : A.in[1] + (size_t)(mb - TP) * D, F.lane, vb);
;               row_finalize(A, F, m, va, 0); row_finalize(A, F, mb, vb, 0); } }
.LBB0_11:
	s_add_u32 s27, s18, s28
	s_add_i32 s34, s27, 1
	s_cmp_lt_i32 s34, s38
	s_cselect_b32 s34, s34, s27
	s_ashr_i32 s35, s34, 31
	v_add_u32_e32 v39, 0x12000, v35
	v_add_u32_e32 v37, 0x13000, v35
	v_mov_b32_e32 v88, 0
	v_mov_b32_e32 v89, 0
	s_waitcnt vmcnt(6)
	v_mov_b64_e32 v[30:31], v[150:151]
	v_mov_b64_e32 v[32:33], v[152:153]
	v_mov_b64_e32 v[26:27], v[154:155]
	v_mov_b64_e32 v[28:29], v[156:157]
	v_mov_b64_e32 v[22:23], v[158:159]
	v_mov_b64_e32 v[24:25], v[160:161]
	v_mov_b64_e32 v[18:19], v[162:163]
	v_mov_b64_e32 v[20:21], v[164:165]
	v_mov_b64_e32 v[14:15], v[166:167]
	v_mov_b64_e32 v[16:17], v[168:169]
	v_mov_b64_e32 v[10:11], v[170:171]
	v_mov_b64_e32 v[12:13], v[172:173]
	v_mov_b64_e32 v[6:7], v[174:175]
	v_mov_b64_e32 v[8:9], v[176:177]
	v_mov_b64_e32 v[2:3], v[178:179]
	v_mov_b64_e32 v[4:5], v[180:181]
	s_add_i32 s41, s38, -1
	s_add_u32 s27, s18, s28
	s_add_i32 s27, s27, 2
	s_add_i32 s41, s38, -1
	s_min_i32 s27, s27, s41
	s_add_i32 s36, s27, 0xffffc000
	s_cmpk_lt_i32 s27, 0x4000
	s_cselect_b32 s36, s27, s36
	s_cselect_b32 s27, 0, 8
	s_mov_b32 s37, 0
	s_add_u32 s40, s20, s27
	s_addc_u32 s41, s21, 0
	s_load_dwordx2 s[40:41], s[40:41], 0x0
	s_lshl_b64 s[36:37], s[36:37], 12
	s_waitcnt lgkmcnt(0)
	s_add_u32 s36, s40, s36
	s_addc_u32 s37, s41, s37
	v_lshl_add_u64 v[182:183], s[36:37], 0, v[50:51]
	global_load_dwordx4 v[150:153], v[182:183], off
	global_load_dwordx4 v[154:157], v[182:183], off offset:16
	global_load_dwordx4 v[158:161], v[182:183], off offset:2048
	global_load_dwordx4 v[162:165], v[182:183], off offset:2064
	s_add_u32 s27, s18, s28
	s_add_i32 s27, s27, 3
	s_add_i32 s41, s38, -1
	s_min_i32 s27, s27, s41
	s_add_i32 s36, s27, 0xffffc000
	s_cmpk_lt_i32 s27, 0x4000
	s_cselect_b32 s36, s27, s36
	s_cselect_b32 s27, 0, 8
	s_mov_b32 s37, 0
	s_add_u32 s40, s20, s27
	s_addc_u32 s41, s21, 0
	s_load_dwordx2 s[40:41], s[40:41], 0x0
	s_lshl_b64 s[36:37], s[36:37], 12
	s_waitcnt lgkmcnt(0)
	s_add_u32 s36, s40, s36
	s_addc_u32 s37, s41, s37
	v_lshl_add_u64 v[182:183], s[36:37], 0, v[50:51]
	global_load_dwordx4 v[166:169], v[182:183], off
	global_load_dwordx4 v[170:173], v[182:183], off offset:16
	global_load_dwordx4 v[174:177], v[182:183], off offset:2048
	global_load_dwordx4 v[178:181], v[182:183], off offset:2064
	s_nop 0
	v_cvt_pk_bf16_f32 v52, v30, v31
	v_cvt_pk_bf16_f32 v53, v32, v33
	s_nop 0
	v_cvt_pk_bf16_f32 v54, v26, v27
	v_cvt_pk_bf16_f32 v55, v28, v29
	global_store_dwordx4 v[46:47], v[52:55], off
	s_nop 0
	s_nop 0
	v_cvt_pk_bf16_f32 v52, v22, v23
	v_cvt_pk_bf16_f32 v53, v24, v25
	s_nop 0
	v_cvt_pk_bf16_f32 v54, v18, v19
	v_cvt_pk_bf16_f32 v55, v20, v21
	ds_read_b128 v[56:59], v39
	ds_read_b128 v[60:63], v39 offset:16
	ds_read_b128 v[64:67], v39 offset:2048
	ds_read_b128 v[68:71], v39 offset:2064
	ds_read_b128 v[72:75], v37
	ds_read_b128 v[76:79], v37 offset:16
	ds_read_b128 v[80:83], v37 offset:2048
	ds_read_b128 v[84:87], v37 offset:2064
	global_store_dwordx4 v[46:47], v[52:55], off offset:1024
	s_waitcnt lgkmcnt(7)
	s_nop 0
	v_mul_f32_e32 v52, v31, v57
	v_mul_f32_e32 v53, v33, v59
	s_waitcnt lgkmcnt(6)
	v_mul_f32_e32 v54, v27, v61
	v_mul_f32_e32 v55, v29, v63
	v_fmac_f32_e32 v52, v30, v56
	v_fmac_f32_e32 v53, v32, v58
	s_waitcnt lgkmcnt(5)
	v_mul_f32_e32 v57, v23, v65
	v_mul_f32_e32 v59, v25, v67
	v_fmac_f32_e32 v54, v26, v60
	v_fmac_f32_e32 v55, v28, v62
	v_add_f32_e32 v52, v52, v53
	s_waitcnt lgkmcnt(4)
	v_mul_f32_e32 v61, v19, v69
	v_mul_f32_e32 v63, v21, v71
	v_fmac_f32_e32 v57, v22, v64
	v_fmac_f32_e32 v59, v24, v66
	v_add_f32_e32 v53, v54, v55
	v_add_f32_e32 v52, 0, v52
	v_fmac_f32_e32 v61, v18, v68
	v_fmac_f32_e32 v63, v20, v70
	v_add_f32_e32 v54, v57, v59
	v_add_f32_e32 v52, v52, v53
	v_add_f32_e32 v55, v61, v63
	v_add_f32_e32 v52, v52, v54
	v_add_f32_e32 v52, v52, v55
	s_waitcnt lgkmcnt(3)
	v_mul_f32_e32 v65, v31, v73
	v_mul_f32_e32 v67, v33, v75
	v_add_f32_dpp v52, v52, v52 quad_perm:[1,0,3,2] row_mask:0xf bank_mask:0xf bound_ctrl:1
	s_waitcnt lgkmcnt(2)
	v_mul_f32_e32 v69, v27, v77
	v_mul_f32_e32 v71, v29, v79
	v_fmac_f32_e32 v65, v30, v72
	v_fmac_f32_e32 v67, v32, v74
	v_add_f32_dpp v52, v52, v52 quad_perm:[2,3,0,1] row_mask:0xf bank_mask:0xf bound_ctrl:1
	s_waitcnt lgkmcnt(1)
	v_mul_f32_e32 v73, v23, v81
	v_mul_f32_e32 v75, v25, v83
	v_fmac_f32_e32 v69, v26, v76
	v_fmac_f32_e32 v71, v28, v78
	v_add_f32_e32 v56, v65, v67
	v_add_f32_dpp v52, v52, v52 row_half_mirror row_mask:0xf bank_mask:0xf bound_ctrl:1
	s_waitcnt lgkmcnt(0)
	v_mul_f32_e32 v77, v19, v85
	v_mul_f32_e32 v79, v21, v87
	v_fmac_f32_e32 v73, v22, v80
	v_fmac_f32_e32 v75, v24, v82
	v_add_f32_e32 v57, v69, v71
	v_add_f32_e32 v56, 0, v56
	v_add_f32_dpp v52, v52, v52 row_mirror row_mask:0xf bank_mask:0xf bound_ctrl:1
	v_fmac_f32_e32 v77, v18, v84
	v_fmac_f32_e32 v79, v20, v86
	v_add_f32_e32 v58, v73, v75
	v_add_f32_e32 v53, v56, v57
	v_mov_b32_dpp v88, v52 row_bcast:15 row_mask:0xa bank_mask:0xf
	v_add_f32_e32 v59, v77, v79
	v_add_f32_e32 v53, v53, v58
	v_add_f32_e32 v52, v52, v88
	v_add_f32_e32 v53, v53, v59
	v_add_u32_e32 v56, 0x14000, v35
	v_mov_b32_dpp v89, v52 row_bcast:31 row_mask:0xc bank_mask:0xf
	v_add_f32_dpp v53, v53, v53 quad_perm:[1,0,3,2] row_mask:0xf bank_mask:0xf bound_ctrl:1
	v_add_f32_e32 v52, v52, v89
	s_nop 0
	v_readlane_b32 s27, v52, 63
	v_add_f32_dpp v52, v53, v53 quad_perm:[2,3,0,1] row_mask:0xf bank_mask:0xf bound_ctrl:1
	v_mov_b32_e32 v53, 0
	s_nop 0
	v_add_f32_dpp v52, v52, v52 row_half_mirror row_mask:0xf bank_mask:0xf bound_ctrl:1
	s_nop 1
	v_add_f32_dpp v52, v52, v52 row_mirror row_mask:0xf bank_mask:0xf bound_ctrl:1
	s_nop 1
	v_mov_b32_dpp v53, v52 row_bcast:15 row_mask:0xa bank_mask:0xf
	v_add_f32_e32 v52, v52, v53
	v_mov_b32_e32 v53, 0
	s_nop 1
	v_mov_b32_dpp v53, v52 row_bcast:31 row_mask:0xc bank_mask:0xf
	v_add_f32_e32 v57, v52, v53
	ds_read_b128 v[52:55], v56
	ds_read_b128 v[58:61], v56 offset:2064
	ds_read_b128 v[62:65], v56 offset:2048
	ds_read_b128 v[66:69], v56 offset:16
	v_readlane_b32 s39, v57, 63
	s_waitcnt lgkmcnt(3)
; #define LAS __attribute__((address_space(3)))
; __device__ __forceinline__ float wave_sum(float v) { return rdlane(dpp_sum63(v), 63); }
; __device__ __forceinline__ void row_finalize(CArgs& A, Frame& F, int m, const f32x4 (&v)[4], int Ln) {
;     ...
;     for (int c = 0; c < 8; ++c) { float s = 0.f;
; #pragma unroll
;         for (int j = 0; j < 4; ++j) { const f32x4 w = *(const LAS f32x4*)(wig + c * 1024 + RCOL(F.lane, j)); s += (v[j][0] * w[0] + v[j][1] * w[1]) + (v[j][2] * w[2] + v[j][3] * w[3]); }
;         r[c] = wave_sum(s); if (c & 1) asm volatile("" ::: "memory"); }
	v_mul_f32_e32 v53, v31, v53
	v_fmac_f32_e32 v53, v30, v52
	v_mul_f32_e32 v52, v33, v55
	v_fmac_f32_e32 v52, v32, v54
	v_add_f32_e32 v52, v53, v52
	s_waitcnt lgkmcnt(0)
	v_mul_f32_e32 v53, v27, v67
	v_mul_f32_e32 v54, v29, v69
	v_fmac_f32_e32 v53, v26, v66
	v_fmac_f32_e32 v54, v28, v68
	v_add_f32_e32 v52, 0, v52
	v_add_f32_e32 v53, v53, v54
	v_add_f32_e32 v52, v53, v52
	v_mul_f32_e32 v53, v23, v63
	v_mul_f32_e32 v54, v25, v65
	v_fmac_f32_e32 v53, v22, v62
	v_fmac_f32_e32 v54, v24, v64
	v_add_f32_e32 v53, v53, v54
	v_add_f32_e32 v52, v53, v52
	v_mul_f32_e32 v53, v19, v59
	v_mul_f32_e32 v54, v21, v61
	v_fmac_f32_e32 v53, v18, v58
	v_fmac_f32_e32 v54, v20, v60
	v_add_f32_e32 v53, v53, v54
	v_add_f32_e32 v52, v53, v52
	v_mov_b32_e32 v53, 0
	v_mov_b32_e32 v54, 0
	v_add_f32_dpp v52, v52, v52 quad_perm:[1,0,3,2] row_mask:0xf bank_mask:0xf bound_ctrl:1
	s_nop 1
	v_add_f32_dpp v52, v52, v52 quad_perm:[2,3,0,1] row_mask:0xf bank_mask:0xf bound_ctrl:1
	s_nop 1
	v_add_f32_dpp v52, v52, v52 row_half_mirror row_mask:0xf bank_mask:0xf bound_ctrl:1
	s_nop 1
	v_add_f32_dpp v52, v52, v52 row_mirror row_mask:0xf bank_mask:0xf bound_ctrl:1
	s_nop 1
	v_mov_b32_dpp v53, v52 row_bcast:15 row_mask:0xa bank_mask:0xf
	v_add_f32_e32 v53, v52, v53
	v_add_u32_e32 v52, 0x15000, v35
	ds_read_b128 v[58:61], v52
	ds_read_b128 v[62:65], v52 offset:16
	v_mov_b32_dpp v54, v53 row_bcast:31 row_mask:0xc bank_mask:0xf
	v_add_f32_e32 v53, v53, v54
	s_waitcnt lgkmcnt(1)
	v_mul_f32_e32 v54, v33, v61
	v_readlane_b32 s40, v53, 63
	v_mul_f32_e32 v53, v31, v59
	v_fmac_f32_e32 v53, v30, v58
	v_fmac_f32_e32 v54, v32, v60
	ds_read_b128 v[58:61], v52 offset:2048
	v_add_f32_e32 v53, v53, v54
	s_waitcnt lgkmcnt(1)
	v_mul_f32_e32 v54, v27, v63
	v_mul_f32_e32 v55, v29, v65
	v_fmac_f32_e32 v54, v26, v62
	v_fmac_f32_e32 v55, v28, v64
	ds_read_b128 v[62:65], v52 offset:2064
	v_add_f32_e32 v53, 0, v53
	v_add_f32_e32 v54, v54, v55
	v_add_f32_e32 v53, v53, v54
	s_waitcnt lgkmcnt(1)
	v_mul_f32_e32 v54, v23, v59
	v_mul_f32_e32 v55, v25, v61
	v_fmac_f32_e32 v54, v22, v58
	v_fmac_f32_e32 v55, v24, v60
	v_add_f32_e32 v54, v54, v55
	v_add_f32_e32 v53, v53, v54
	s_waitcnt lgkmcnt(0)
	v_mul_f32_e32 v54, v19, v63
	v_mul_f32_e32 v55, v21, v65
	v_fmac_f32_e32 v54, v18, v62
	v_fmac_f32_e32 v55, v20, v64
	v_add_f32_e32 v54, v54, v55
	v_add_f32_e32 v53, v53, v54
	v_mov_b32_e32 v54, 0
	v_mov_b32_e32 v55, 0
	v_add_f32_dpp v53, v53, v53 quad_perm:[1,0,3,2] row_mask:0xf bank_mask:0xf bound_ctrl:1
	s_nop 1
	v_add_f32_dpp v53, v53, v53 quad_perm:[2,3,0,1] row_mask:0xf bank_mask:0xf bound_ctrl:1
	s_nop 1
	v_add_f32_dpp v53, v53, v53 row_half_mirror row_mask:0xf bank_mask:0xf bound_ctrl:1
	s_nop 1
	v_add_f32_dpp v53, v53, v53 row_mirror row_mask:0xf bank_mask:0xf bound_ctrl:1
	s_nop 1
	v_mov_b32_dpp v54, v53 row_bcast:15 row_mask:0xa bank_mask:0xf
	v_add_f32_e32 v54, v53, v54
	v_add_u32_e32 v53, 0x16000, v35
	ds_read_b128 v[58:61], v53
	ds_read_b128 v[62:65], v53 offset:16
	v_mov_b32_dpp v55, v54 row_bcast:31 row_mask:0xc bank_mask:0xf
	v_add_f32_e32 v54, v54, v55
	s_waitcnt lgkmcnt(1)
	v_mul_f32_e32 v55, v33, v61
	v_readlane_b32 s41, v54, 63
	v_mul_f32_e32 v54, v31, v59
	v_fmac_f32_e32 v54, v30, v58
	v_fmac_f32_e32 v55, v32, v60
	ds_read_b128 v[58:61], v53 offset:2048
	v_add_f32_e32 v54, v54, v55
	s_waitcnt lgkmcnt(1)
	v_mul_f32_e32 v55, v27, v63
	v_mul_f32_e32 v57, v29, v65
	v_fmac_f32_e32 v55, v26, v62
	v_fmac_f32_e32 v57, v28, v64
	ds_read_b128 v[62:65], v53 offset:2064
	v_add_f32_e32 v54, 0, v54
	v_add_f32_e32 v55, v55, v57
	v_add_f32_e32 v54, v54, v55
	s_waitcnt lgkmcnt(1)
	v_mul_f32_e32 v55, v23, v59
	v_mul_f32_e32 v57, v25, v61
	v_fmac_f32_e32 v55, v22, v58
	v_fmac_f32_e32 v57, v24, v60
	v_add_f32_e32 v55, v55, v57
	v_add_f32_e32 v54, v54, v55
	s_waitcnt lgkmcnt(0)
	v_mul_f32_e32 v55, v19, v63
	v_mul_f32_e32 v57, v21, v65
	v_fmac_f32_e32 v55, v18, v62
	v_fmac_f32_e32 v57, v20, v64
	v_add_f32_e32 v55, v55, v57
	v_add_f32_e32 v54, v54, v55
	v_mov_b32_e32 v55, 0
	v_mov_b32_e32 v57, 0
	v_add_f32_dpp v54, v54, v54 quad_perm:[1,0,3,2] row_mask:0xf bank_mask:0xf bound_ctrl:1
	s_nop 1
	v_add_f32_dpp v54, v54, v54 quad_perm:[2,3,0,1] row_mask:0xf bank_mask:0xf bound_ctrl:1
	s_nop 1
	v_add_f32_dpp v54, v54, v54 row_half_mirror row_mask:0xf bank_mask:0xf bound_ctrl:1
	s_nop 1
	v_add_f32_dpp v54, v54, v54 row_mirror row_mask:0xf bank_mask:0xf bound_ctrl:1
	s_nop 1
	v_mov_b32_dpp v55, v54 row_bcast:15 row_mask:0xa bank_mask:0xf
	v_add_f32_e32 v55, v54, v55
	v_add_u32_e32 v54, 0x17000, v35
	ds_read_b128 v[58:61], v54
	ds_read_b128 v[62:65], v54 offset:16
	v_mov_b32_dpp v57, v55 row_bcast:31 row_mask:0xc bank_mask:0xf
	v_add_f32_e32 v55, v55, v57
	s_waitcnt lgkmcnt(1)
	v_mul_f32_e32 v57, v33, v61
	v_readlane_b32 s42, v55, 63
	v_mul_f32_e32 v55, v31, v59
	v_fmac_f32_e32 v55, v30, v58
	v_fmac_f32_e32 v57, v32, v60
	ds_read_b128 v[58:61], v54 offset:2048
	v_add_f32_e32 v55, v55, v57
	s_waitcnt lgkmcnt(1)
	v_mul_f32_e32 v57, v27, v63
	v_fmac_f32_e32 v57, v26, v62
	v_mul_f32_e32 v62, v29, v65
	v_fmac_f32_e32 v62, v28, v64
	v_add_f32_e32 v55, 0, v55
	v_add_f32_e32 v57, v57, v62
	ds_read_b128 v[62:65], v54 offset:2064
	v_add_f32_e32 v55, v55, v57
	s_waitcnt lgkmcnt(1)
	v_mul_f32_e32 v57, v23, v59
	v_fmac_f32_e32 v57, v22, v58
	v_mul_f32_e32 v58, v25, v61
	v_fmac_f32_e32 v58, v24, v60
	v_add_f32_e32 v57, v57, v58
	v_add_f32_e32 v55, v55, v57
	s_waitcnt lgkmcnt(0)
; #define LAS __attribute__((address_space(3)))
; __device__ __forceinline__ float wave_sum(float v) { return rdlane(dpp_sum63(v), 63); }
; __device__ __forceinline__ void row_finalize(CArgs& A, Frame& F, int m, const f32x4 (&v)[4], int Ln) {
;     ...
;     for (int c = 0; c < 8; ++c) { float s = 0.f;
; #pragma unroll
;         for (int j = 0; j < 4; ++j) { const f32x4 w = *(const LAS f32x4*)(wig + c * 1024 + RCOL(F.lane, j)); s += (v[j][0] * w[0] + v[j][1] * w[1]) + (v[j][2] * w[2] + v[j][3] * w[3]); }
;         r[c] = wave_sum(s); if (c & 1) asm volatile("" ::: "memory"); }
;     if (F.lane < 8) { float x = r[0];
; #pragma unroll
;         for (int c = 1; c < 8; ++c) x = (F.lane == c) ? r[c] : x;
;         WSP(float, WS_IGFG)[(size_t)m * 8 + F.lane] = x + b_in[F.lane]; }
	v_mul_f32_e32 v57, v19, v63
	v_mul_f32_e32 v58, v21, v65
	v_fmac_f32_e32 v57, v18, v62
	v_fmac_f32_e32 v58, v20, v64
	v_add_f32_e32 v57, v57, v58
	v_add_f32_e32 v55, v55, v57
	v_mov_b32_e32 v57, 0
	s_nop 0
	v_add_f32_dpp v55, v55, v55 quad_perm:[1,0,3,2] row_mask:0xf bank_mask:0xf bound_ctrl:1
	s_nop 1
	v_add_f32_dpp v55, v55, v55 quad_perm:[2,3,0,1] row_mask:0xf bank_mask:0xf bound_ctrl:1
	s_nop 1
	v_add_f32_dpp v55, v55, v55 row_half_mirror row_mask:0xf bank_mask:0xf bound_ctrl:1
	s_nop 1
	v_add_f32_dpp v55, v55, v55 row_mirror row_mask:0xf bank_mask:0xf bound_ctrl:1
	s_nop 1
	v_mov_b32_dpp v57, v55 row_bcast:15 row_mask:0xa bank_mask:0xf
	v_add_f32_e32 v55, v55, v57
	v_mov_b32_e32 v57, 0
	s_nop 1
	v_mov_b32_dpp v57, v55 row_bcast:31 row_mask:0xc bank_mask:0xf
	v_add_f32_e32 v55, v55, v57
	v_add_u32_e32 v57, 0x18000, v35
	ds_read_b128 v[58:61], v57
	ds_read_b128 v[62:65], v57 offset:2064
	ds_read_b128 v[66:69], v57 offset:2048
	ds_read_b128 v[70:73], v57 offset:16
	v_readlane_b32 s43, v55, 63
	s_waitcnt lgkmcnt(3)
	v_mul_f32_e32 v55, v31, v59
	v_fmac_f32_e32 v55, v30, v58
	v_mul_f32_e32 v58, v33, v61
	v_fmac_f32_e32 v58, v32, v60
	v_add_f32_e32 v55, v55, v58
	s_waitcnt lgkmcnt(0)
	v_mul_f32_e32 v58, v27, v71
	v_mul_f32_e32 v59, v29, v73
	v_fmac_f32_e32 v58, v26, v70
	v_fmac_f32_e32 v59, v28, v72
	v_add_f32_e32 v55, 0, v55
	v_add_f32_e32 v58, v58, v59
	v_add_f32_e32 v55, v58, v55
	v_mul_f32_e32 v58, v23, v67
	v_mul_f32_e32 v59, v25, v69
	v_fmac_f32_e32 v58, v22, v66
	v_fmac_f32_e32 v59, v24, v68
	v_add_f32_e32 v58, v58, v59
	v_add_f32_e32 v55, v58, v55
	v_mul_f32_e32 v58, v19, v63
	v_mul_f32_e32 v59, v21, v65
	v_fmac_f32_e32 v58, v18, v62
	v_fmac_f32_e32 v59, v20, v64
	v_add_f32_e32 v58, v58, v59
	v_add_f32_e32 v55, v58, v55
	v_mov_b32_e32 v58, 0
	v_mov_b32_e32 v63, 0
	v_add_f32_dpp v55, v55, v55 quad_perm:[1,0,3,2] row_mask:0xf bank_mask:0xf bound_ctrl:1
	s_nop 1
	v_add_f32_dpp v55, v55, v55 quad_perm:[2,3,0,1] row_mask:0xf bank_mask:0xf bound_ctrl:1
	s_nop 1
	v_add_f32_dpp v55, v55, v55 row_half_mirror row_mask:0xf bank_mask:0xf bound_ctrl:1
	s_nop 1
	v_add_f32_dpp v55, v55, v55 row_mirror row_mask:0xf bank_mask:0xf bound_ctrl:1
	s_nop 1
	v_mov_b32_dpp v58, v55 row_bcast:15 row_mask:0xa bank_mask:0xf
	v_add_f32_e32 v62, v55, v58
	v_add_u32_e32 v55, 0x19000, v35
	ds_read_b128 v[58:61], v55
	v_mov_b32_dpp v63, v62 row_bcast:31 row_mask:0xc bank_mask:0xf
	v_add_f32_e32 v62, v62, v63
	s_nop 0
	v_readlane_b32 s44, v62, 63
	ds_read_b128 v[62:65], v55 offset:16
	s_waitcnt lgkmcnt(1)
	v_mul_f32_e32 v31, v31, v59
	v_fmac_f32_e32 v31, v30, v58
	v_mul_f32_e32 v30, v33, v61
	v_fmac_f32_e32 v30, v32, v60
	s_waitcnt lgkmcnt(0)
	v_mul_f32_e32 v27, v27, v63
	v_fmac_f32_e32 v27, v26, v62
	v_mul_f32_e32 v26, v29, v65
	v_add_f32_e32 v30, v31, v30
	v_fmac_f32_e32 v26, v28, v64
	v_add_f32_e32 v58, 0, v30
	ds_read_b128 v[30:33], v55 offset:2048
	v_add_f32_e32 v26, v27, v26
	v_add_f32_e32 v58, v58, v26
	ds_read_b128 v[26:29], v55 offset:2064
	s_waitcnt lgkmcnt(1)
	v_mul_f32_e32 v23, v23, v31
	v_fmac_f32_e32 v23, v22, v30
	v_mul_f32_e32 v22, v25, v33
	s_waitcnt lgkmcnt(0)
	v_mul_f32_e32 v19, v19, v27
	v_fmac_f32_e32 v22, v24, v32
	v_fmac_f32_e32 v19, v18, v26
	v_mul_f32_e32 v18, v21, v29
	v_add_f32_e32 v22, v23, v22
	v_fmac_f32_e32 v18, v20, v28
	v_add_f32_e32 v22, v58, v22
	v_add_f32_e32 v18, v19, v18
	v_add_f32_e32 v18, v22, v18
	v_mov_b32_e32 v19, 0
	s_nop 0
	v_add_f32_dpp v18, v18, v18 quad_perm:[1,0,3,2] row_mask:0xf bank_mask:0xf bound_ctrl:1
	s_nop 1
	v_add_f32_dpp v18, v18, v18 quad_perm:[2,3,0,1] row_mask:0xf bank_mask:0xf bound_ctrl:1
	s_nop 1
	v_add_f32_dpp v18, v18, v18 row_half_mirror row_mask:0xf bank_mask:0xf bound_ctrl:1
	s_nop 1
	v_add_f32_dpp v18, v18, v18 row_mirror row_mask:0xf bank_mask:0xf bound_ctrl:1
	s_nop 1
	v_mov_b32_dpp v19, v18 row_bcast:15 row_mask:0xa bank_mask:0xf
	v_add_f32_e32 v18, v18, v19
	v_mov_b32_e32 v19, 0
	s_nop 1
	v_mov_b32_dpp v19, v18 row_bcast:31 row_mask:0xc bank_mask:0xf
	v_add_f32_e32 v18, v18, v19
	s_nop 0
	v_readlane_b32 s45, v18, 63
	s_and_saveexec_b64 s[36:37], vcc
	s_cbranch_execz .LBB0_13
	v_mov_b32_e32 v18, v149
	v_mov_b32_e32 v19, s27
	v_mov_b32_e32 v20, s39
	v_cndmask_b32_e64 v19, v19, v20, s[16:17]
	v_mov_b32_e32 v20, s40
	v_cndmask_b32_e64 v19, v19, v20, s[4:5]
	v_mov_b32_e32 v20, s41
	v_cndmask_b32_e64 v19, v19, v20, s[6:7]
	v_mov_b32_e32 v20, s42
	v_cndmask_b32_e64 v19, v19, v20, s[8:9]
	v_mov_b32_e32 v20, s43
	v_cndmask_b32_e64 v19, v19, v20, s[10:11]
	v_mov_b32_e32 v20, s44
	v_cndmask_b32_e64 v19, v19, v20, s[12:13]
	v_mov_b32_e32 v20, s45
	v_cndmask_b32_e64 v19, v19, v20, s[14:15]
	s_nop 0
	v_add_f32_e32 v18, v19, v18
	global_store_dword v[48:49], v18, off
; #define LAS __attribute__((address_space(3)))
; __device__ __forceinline__ float wave_sum(float v) { return rdlane(dpp_sum63(v), 63); }
; __device__ __forceinline__ void row_finalize(CArgs& A, Frame& F, int m, const f32x4 (&v)[4], int Ln) {
;     row_store_bf(WSP(bf16, WS_X) + (size_t)m * D, F.lane, v);
;     const LAS float* wig = (const LAS float*)(F.lds + WIG_OFF); const float* b_in = A.in[10] + (size_t)Ln * DIN + 3072;
;     float r[8];
; #pragma unroll
;     for (int c = 0; c < 8; ++c) { float s = 0.f;
; #pragma unroll
;         for (int j = 0; j < 4; ++j) { const f32x4 w = *(const LAS f32x4*)(wig + c * 1024 + RCOL(F.lane, j)); s += (v[j][0] * w[0] + v[j][1] * w[1]) + (v[j][2] * w[2] + v[j][3] * w[3]); }
;         r[c] = wave_sum(s); if (c & 1) asm volatile("" ::: "memory"); }
.LBB0_13:
	s_or_b64 exec, exec, s[36:37]
	s_lshl_b64 s[36:37], s[34:35], 11
	v_lshl_add_u64 v[26:27], v[40:41], 0, s[36:37]
	s_nop 0
	v_cvt_pk_bf16_f32 v18, v14, v15
	v_cvt_pk_bf16_f32 v19, v16, v17
	v_cvt_pk_bf16_f32 v20, v10, v11
	v_cvt_pk_bf16_f32 v21, v12, v13
	global_store_dwordx4 v[26:27], v[18:21], off
	s_nop 0
	s_nop 0
	v_cvt_pk_bf16_f32 v18, v6, v7
	v_cvt_pk_bf16_f32 v19, v8, v9
	v_cvt_pk_bf16_f32 v20, v2, v3
	v_cvt_pk_bf16_f32 v21, v4, v5
	ds_read_b128 v[22:25], v39
	global_store_dwordx4 v[26:27], v[18:21], off offset:1024
	ds_read_b128 v[18:21], v39 offset:16
	s_waitcnt lgkmcnt(1)
	v_mul_f32_e32 v23, v15, v23
	v_fmac_f32_e32 v23, v14, v22
	v_mul_f32_e32 v22, v17, v25
	s_waitcnt lgkmcnt(0)
	v_mul_f32_e32 v19, v11, v19
	v_fmac_f32_e32 v22, v16, v24
	v_fmac_f32_e32 v19, v10, v18
	v_mul_f32_e32 v18, v13, v21
	v_add_f32_e32 v22, v23, v22
	v_fmac_f32_e32 v18, v12, v20
	v_add_f32_e32 v26, 0, v22
	ds_read_b128 v[22:25], v39 offset:2048
	v_add_f32_e32 v18, v19, v18
	v_add_f32_e32 v26, v26, v18
	ds_read_b128 v[18:21], v39 offset:2064
	s_waitcnt lgkmcnt(1)
	v_mul_f32_e32 v23, v7, v23
	v_fmac_f32_e32 v23, v6, v22
	v_mul_f32_e32 v22, v9, v25
	s_waitcnt lgkmcnt(0)
	v_mul_f32_e32 v19, v3, v19
	v_fmac_f32_e32 v22, v8, v24
	v_fmac_f32_e32 v19, v2, v18
	v_mul_f32_e32 v18, v5, v21
	v_add_f32_e32 v22, v23, v22
	v_fmac_f32_e32 v18, v4, v20
	v_add_f32_e32 v22, v26, v22
	v_add_f32_e32 v18, v19, v18
	v_add_f32_e32 v18, v22, v18
	v_mov_b32_e32 v19, 0
	v_mov_b32_e32 v23, 0
	v_add_f32_dpp v18, v18, v18 quad_perm:[1,0,3,2] row_mask:0xf bank_mask:0xf bound_ctrl:1
	s_nop 1
	v_add_f32_dpp v18, v18, v18 quad_perm:[2,3,0,1] row_mask:0xf bank_mask:0xf bound_ctrl:1
	s_nop 1
	v_add_f32_dpp v18, v18, v18 row_half_mirror row_mask:0xf bank_mask:0xf bound_ctrl:1
	s_nop 1
	v_add_f32_dpp v18, v18, v18 row_mirror row_mask:0xf bank_mask:0xf bound_ctrl:1
	s_nop 1
	v_mov_b32_dpp v19, v18 row_bcast:15 row_mask:0xa bank_mask:0xf
	v_add_f32_e32 v22, v18, v19
	ds_read_b128 v[18:21], v37
	s_nop 0
	v_mov_b32_dpp v23, v22 row_bcast:31 row_mask:0xc bank_mask:0xf
	v_add_f32_e32 v22, v22, v23
	s_nop 0
	v_readlane_b32 s27, v22, 63
	ds_read_b128 v[22:25], v37 offset:16
	s_waitcnt lgkmcnt(1)
	v_mul_f32_e32 v19, v15, v19
	v_fmac_f32_e32 v19, v14, v18
	v_mul_f32_e32 v18, v17, v21
	v_fmac_f32_e32 v18, v16, v20
	v_add_f32_e32 v18, v19, v18
	s_waitcnt lgkmcnt(0)
	v_mul_f32_e32 v23, v11, v23
	v_add_f32_e32 v26, 0, v18
	v_fmac_f32_e32 v23, v10, v22
	v_mul_f32_e32 v22, v13, v25
	ds_read_b128 v[18:21], v37 offset:2048
	v_fmac_f32_e32 v22, v12, v24
	v_add_f32_e32 v22, v23, v22
	v_add_f32_e32 v26, v26, v22
	ds_read_b128 v[22:25], v37 offset:2064
	s_waitcnt lgkmcnt(1)
	v_mul_f32_e32 v19, v7, v19
	v_fmac_f32_e32 v19, v6, v18
	v_mul_f32_e32 v18, v9, v21
	v_fmac_f32_e32 v18, v8, v20
	v_add_f32_e32 v18, v19, v18
	s_waitcnt lgkmcnt(0)
	v_mul_f32_e32 v19, v3, v23
	v_mul_f32_e32 v20, v5, v25
	v_fmac_f32_e32 v19, v2, v22
	v_fmac_f32_e32 v20, v4, v24
	v_add_f32_e32 v18, v26, v18
	v_add_f32_e32 v19, v19, v20
	v_add_f32_e32 v18, v18, v19
	v_mov_b32_e32 v19, 0
	s_nop 0
	v_add_f32_dpp v18, v18, v18 quad_perm:[1,0,3,2] row_mask:0xf bank_mask:0xf bound_ctrl:1
	s_nop 1
	v_add_f32_dpp v18, v18, v18 quad_perm:[2,3,0,1] row_mask:0xf bank_mask:0xf bound_ctrl:1
	s_nop 1
	v_add_f32_dpp v18, v18, v18 row_half_mirror row_mask:0xf bank_mask:0xf bound_ctrl:1
	s_nop 1
	v_add_f32_dpp v18, v18, v18 row_mirror row_mask:0xf bank_mask:0xf bound_ctrl:1
	s_nop 1
	v_mov_b32_dpp v19, v18 row_bcast:15 row_mask:0xa bank_mask:0xf
	v_add_f32_e32 v18, v18, v19
	v_mov_b32_e32 v19, 0
	s_nop 1
	v_mov_b32_dpp v19, v18 row_bcast:31 row_mask:0xc bank_mask:0xf
	v_add_f32_e32 v22, v18, v19
	ds_read_b128 v[18:21], v56
	v_readlane_b32 s39, v22, 63
	ds_read_b128 v[22:25], v56 offset:2064
	ds_read_b128 v[26:29], v56 offset:2048
	ds_read_b128 v[30:33], v56 offset:16
	s_waitcnt lgkmcnt(3)
	v_mul_f32_e32 v19, v15, v19
	v_fmac_f32_e32 v19, v14, v18
	v_mul_f32_e32 v18, v17, v21
	v_fmac_f32_e32 v18, v16, v20
	v_add_f32_e32 v18, v19, v18
	s_waitcnt lgkmcnt(0)
	v_mul_f32_e32 v19, v11, v31
	v_mul_f32_e32 v20, v13, v33
	v_fmac_f32_e32 v19, v10, v30
	v_fmac_f32_e32 v20, v12, v32
	v_add_f32_e32 v18, 0, v18
	v_add_f32_e32 v19, v19, v20
	v_add_f32_e32 v18, v19, v18
	v_mul_f32_e32 v19, v7, v27
	v_mul_f32_e32 v20, v9, v29
	v_fmac_f32_e32 v19, v6, v26
	v_fmac_f32_e32 v20, v8, v28
	v_add_f32_e32 v19, v19, v20
	v_add_f32_e32 v18, v19, v18
	v_mul_f32_e32 v19, v3, v23
	v_mul_f32_e32 v20, v5, v25
	v_fmac_f32_e32 v19, v2, v22
	v_fmac_f32_e32 v20, v4, v24
	v_add_f32_e32 v19, v19, v20
	v_add_f32_e32 v18, v19, v18
	v_mov_b32_e32 v19, 0
	v_mov_b32_e32 v23, 0
	v_add_f32_dpp v18, v18, v18 quad_perm:[1,0,3,2] row_mask:0xf bank_mask:0xf bound_ctrl:1
	s_nop 1
	v_add_f32_dpp v18, v18, v18 quad_perm:[2,3,0,1] row_mask:0xf bank_mask:0xf bound_ctrl:1
	s_nop 1
	v_add_f32_dpp v18, v18, v18 row_half_mirror row_mask:0xf bank_mask:0xf bound_ctrl:1
	s_nop 1
	v_add_f32_dpp v18, v18, v18 row_mirror row_mask:0xf bank_mask:0xf bound_ctrl:1
	s_nop 1
	v_mov_b32_dpp v19, v18 row_bcast:15 row_mask:0xa bank_mask:0xf
	v_add_f32_e32 v22, v18, v19
	ds_read_b128 v[18:21], v52
	s_nop 0
	v_mov_b32_dpp v23, v22 row_bcast:31 row_mask:0xc bank_mask:0xf
	v_add_f32_e32 v22, v22, v23
	s_nop 0
	v_readlane_b32 s40, v22, 63
	ds_read_b128 v[22:25], v52 offset:16
	s_waitcnt lgkmcnt(1)
	v_mul_f32_e32 v19, v15, v19
	v_fmac_f32_e32 v19, v14, v18
	v_mul_f32_e32 v18, v17, v21
	v_fmac_f32_e32 v18, v16, v20
	v_add_f32_e32 v18, v19, v18
	s_waitcnt lgkmcnt(0)
	v_mul_f32_e32 v23, v11, v23
	v_add_f32_e32 v26, 0, v18
	v_fmac_f32_e32 v23, v10, v22
	v_mul_f32_e32 v22, v13, v25
	ds_read_b128 v[18:21], v52 offset:2048
	v_fmac_f32_e32 v22, v12, v24
	v_add_f32_e32 v22, v23, v22
	v_add_f32_e32 v26, v26, v22
	ds_read_b128 v[22:25], v52 offset:2064
	s_waitcnt lgkmcnt(1)
; #define LAS __attribute__((address_space(3)))
; __device__ __forceinline__ float wave_sum(float v) { return rdlane(dpp_sum63(v), 63); }
; __device__ __forceinline__ void row_finalize(CArgs& A, Frame& F, int m, const f32x4 (&v)[4], int Ln) {
;     ...
;     for (int c = 0; c < 8; ++c) { float s = 0.f;
; #pragma unroll
;         for (int j = 0; j < 4; ++j) { const f32x4 w = *(const LAS f32x4*)(wig + c * 1024 + RCOL(F.lane, j)); s += (v[j][0] * w[0] + v[j][1] * w[1]) + (v[j][2] * w[2] + v[j][3] * w[3]); }
;         r[c] = wave_sum(s); if (c & 1) asm volatile("" ::: "memory"); }
	v_mul_f32_e32 v19, v7, v19
	v_fmac_f32_e32 v19, v6, v18
	v_mul_f32_e32 v18, v9, v21
	v_fmac_f32_e32 v18, v8, v20
	v_add_f32_e32 v18, v19, v18
	s_waitcnt lgkmcnt(0)
	v_mul_f32_e32 v19, v3, v23
	v_mul_f32_e32 v20, v5, v25
	v_fmac_f32_e32 v19, v2, v22
	v_fmac_f32_e32 v20, v4, v24
	v_add_f32_e32 v18, v26, v18
	v_add_f32_e32 v19, v19, v20
	v_add_f32_e32 v18, v18, v19
	v_mov_b32_e32 v19, 0
	v_mov_b32_e32 v23, 0
	v_add_f32_dpp v18, v18, v18 quad_perm:[1,0,3,2] row_mask:0xf bank_mask:0xf bound_ctrl:1
	s_nop 1
	v_add_f32_dpp v18, v18, v18 quad_perm:[2,3,0,1] row_mask:0xf bank_mask:0xf bound_ctrl:1
	s_nop 1
	v_add_f32_dpp v18, v18, v18 row_half_mirror row_mask:0xf bank_mask:0xf bound_ctrl:1
	s_nop 1
	v_add_f32_dpp v18, v18, v18 row_mirror row_mask:0xf bank_mask:0xf bound_ctrl:1
	s_nop 1
	v_mov_b32_dpp v19, v18 row_bcast:15 row_mask:0xa bank_mask:0xf
	v_add_f32_e32 v22, v18, v19
	ds_read_b128 v[18:21], v53
	s_nop 0
	v_mov_b32_dpp v23, v22 row_bcast:31 row_mask:0xc bank_mask:0xf
	v_add_f32_e32 v22, v22, v23
	s_nop 0
	v_readlane_b32 s41, v22, 63
	ds_read_b128 v[22:25], v53 offset:16
	s_waitcnt lgkmcnt(1)
	v_mul_f32_e32 v19, v15, v19
	v_fmac_f32_e32 v19, v14, v18
	v_mul_f32_e32 v18, v17, v21
	v_fmac_f32_e32 v18, v16, v20
	v_add_f32_e32 v18, v19, v18
	s_waitcnt lgkmcnt(0)
	v_mul_f32_e32 v23, v11, v23
	v_add_f32_e32 v26, 0, v18
	v_fmac_f32_e32 v23, v10, v22
	v_mul_f32_e32 v22, v13, v25
	ds_read_b128 v[18:21], v53 offset:2048
	v_fmac_f32_e32 v22, v12, v24
	v_add_f32_e32 v22, v23, v22
	v_add_f32_e32 v26, v26, v22
	ds_read_b128 v[22:25], v53 offset:2064
	s_waitcnt lgkmcnt(1)
	v_mul_f32_e32 v19, v7, v19
	v_fmac_f32_e32 v19, v6, v18
	v_mul_f32_e32 v18, v9, v21
	v_fmac_f32_e32 v18, v8, v20
	v_add_f32_e32 v18, v19, v18
	s_waitcnt lgkmcnt(0)
	v_mul_f32_e32 v19, v3, v23
	v_mul_f32_e32 v20, v5, v25
	v_fmac_f32_e32 v19, v2, v22
	v_fmac_f32_e32 v20, v4, v24
	v_add_f32_e32 v18, v26, v18
	v_add_f32_e32 v19, v19, v20
	v_add_f32_e32 v18, v18, v19
	v_mov_b32_e32 v19, 0
	v_mov_b32_e32 v23, 0
	v_add_f32_dpp v18, v18, v18 quad_perm:[1,0,3,2] row_mask:0xf bank_mask:0xf bound_ctrl:1
	s_nop 1
	v_add_f32_dpp v18, v18, v18 quad_perm:[2,3,0,1] row_mask:0xf bank_mask:0xf bound_ctrl:1
	s_nop 1
	v_add_f32_dpp v18, v18, v18 row_half_mirror row_mask:0xf bank_mask:0xf bound_ctrl:1
	s_nop 1
	v_add_f32_dpp v18, v18, v18 row_mirror row_mask:0xf bank_mask:0xf bound_ctrl:1
	s_nop 1
	v_mov_b32_dpp v19, v18 row_bcast:15 row_mask:0xa bank_mask:0xf
	v_add_f32_e32 v22, v18, v19
	ds_read_b128 v[18:21], v54
	s_nop 0
	v_mov_b32_dpp v23, v22 row_bcast:31 row_mask:0xc bank_mask:0xf
	v_add_f32_e32 v22, v22, v23
	s_nop 0
	v_readlane_b32 s42, v22, 63
	ds_read_b128 v[22:25], v54 offset:16
	s_waitcnt lgkmcnt(1)
	v_mul_f32_e32 v19, v15, v19
	v_fmac_f32_e32 v19, v14, v18
	v_mul_f32_e32 v18, v17, v21
	v_fmac_f32_e32 v18, v16, v20
	v_add_f32_e32 v18, v19, v18
	s_waitcnt lgkmcnt(0)
	v_mul_f32_e32 v23, v11, v23
	v_add_f32_e32 v26, 0, v18
	v_fmac_f32_e32 v23, v10, v22
	v_mul_f32_e32 v22, v13, v25
	ds_read_b128 v[18:21], v54 offset:2048
	v_fmac_f32_e32 v22, v12, v24
	v_add_f32_e32 v22, v23, v22
	v_add_f32_e32 v26, v26, v22
	ds_read_b128 v[22:25], v54 offset:2064
	s_waitcnt lgkmcnt(1)
	v_mul_f32_e32 v19, v7, v19
	v_fmac_f32_e32 v19, v6, v18
	v_mul_f32_e32 v18, v9, v21
	v_fmac_f32_e32 v18, v8, v20
	v_add_f32_e32 v18, v19, v18
	s_waitcnt lgkmcnt(0)
	v_mul_f32_e32 v19, v3, v23
	v_mul_f32_e32 v20, v5, v25
	v_fmac_f32_e32 v19, v2, v22
	v_fmac_f32_e32 v20, v4, v24
	v_add_f32_e32 v18, v26, v18
	v_add_f32_e32 v19, v19, v20
	v_add_f32_e32 v18, v18, v19
	v_mov_b32_e32 v19, 0
	s_nop 0
	v_add_f32_dpp v18, v18, v18 quad_perm:[1,0,3,2] row_mask:0xf bank_mask:0xf bound_ctrl:1
	s_nop 1
	v_add_f32_dpp v18, v18, v18 quad_perm:[2,3,0,1] row_mask:0xf bank_mask:0xf bound_ctrl:1
	s_nop 1
	v_add_f32_dpp v18, v18, v18 row_half_mirror row_mask:0xf bank_mask:0xf bound_ctrl:1
	s_nop 1
	v_add_f32_dpp v18, v18, v18 row_mirror row_mask:0xf bank_mask:0xf bound_ctrl:1
	s_nop 1
	v_mov_b32_dpp v19, v18 row_bcast:15 row_mask:0xa bank_mask:0xf
	v_add_f32_e32 v18, v18, v19
	v_mov_b32_e32 v19, 0
	s_nop 1
	v_mov_b32_dpp v19, v18 row_bcast:31 row_mask:0xc bank_mask:0xf
	v_add_f32_e32 v22, v18, v19
	ds_read_b128 v[18:21], v57
	v_readlane_b32 s43, v22, 63
	ds_read_b128 v[22:25], v57 offset:2064
	ds_read_b128 v[26:29], v57 offset:2048
	ds_read_b128 v[30:33], v57 offset:16
	s_waitcnt lgkmcnt(3)
; #define LAS __attribute__((address_space(3)))
; __device__ __forceinline__ float wave_sum(float v) { return rdlane(dpp_sum63(v), 63); }
; __device__ __forceinline__ void row_finalize(CArgs& A, Frame& F, int m, const f32x4 (&v)[4], int Ln) {
;     ...
;     for (int c = 0; c < 8; ++c) { float s = 0.f;
; #pragma unroll
;         for (int j = 0; j < 4; ++j) { const f32x4 w = *(const LAS f32x4*)(wig + c * 1024 + RCOL(F.lane, j)); s += (v[j][0] * w[0] + v[j][1] * w[1]) + (v[j][2] * w[2] + v[j][3] * w[3]); }
;         r[c] = wave_sum(s); if (c & 1) asm volatile("" ::: "memory"); }
;     if (F.lane < 8) { float x = r[0];
; #pragma unroll
;         for (int c = 1; c < 8; ++c) x = (F.lane == c) ? r[c] : x;
;         WSP(float, WS_IGFG)[(size_t)m * 8 + F.lane] = x + b_in[F.lane]; }
	v_mul_f32_e32 v19, v15, v19
	v_fmac_f32_e32 v19, v14, v18
	v_mul_f32_e32 v18, v17, v21
	v_fmac_f32_e32 v18, v16, v20
	v_add_f32_e32 v18, v19, v18
	s_waitcnt lgkmcnt(0)
	v_mul_f32_e32 v19, v11, v31
	v_mul_f32_e32 v20, v13, v33
	v_fmac_f32_e32 v19, v10, v30
	v_fmac_f32_e32 v20, v12, v32
	v_add_f32_e32 v18, 0, v18
	v_add_f32_e32 v19, v19, v20
	v_add_f32_e32 v18, v19, v18
	v_mul_f32_e32 v19, v7, v27
	v_mul_f32_e32 v20, v9, v29
	v_fmac_f32_e32 v19, v6, v26
	v_fmac_f32_e32 v20, v8, v28
	v_add_f32_e32 v19, v19, v20
	v_add_f32_e32 v18, v19, v18
	v_mul_f32_e32 v19, v3, v23
	v_mul_f32_e32 v20, v5, v25
	v_fmac_f32_e32 v19, v2, v22
	v_fmac_f32_e32 v20, v4, v24
	v_add_f32_e32 v19, v19, v20
	v_add_f32_e32 v18, v19, v18
	v_mov_b32_e32 v19, 0
	v_mov_b32_e32 v23, 0
	v_add_f32_dpp v18, v18, v18 quad_perm:[1,0,3,2] row_mask:0xf bank_mask:0xf bound_ctrl:1
	s_nop 1
	v_add_f32_dpp v18, v18, v18 quad_perm:[2,3,0,1] row_mask:0xf bank_mask:0xf bound_ctrl:1
	s_nop 1
	v_add_f32_dpp v18, v18, v18 row_half_mirror row_mask:0xf bank_mask:0xf bound_ctrl:1
	s_nop 1
	v_add_f32_dpp v18, v18, v18 row_mirror row_mask:0xf bank_mask:0xf bound_ctrl:1
	s_nop 1
	v_mov_b32_dpp v19, v18 row_bcast:15 row_mask:0xa bank_mask:0xf
	v_add_f32_e32 v22, v18, v19
	ds_read_b128 v[18:21], v55
	s_nop 0
	v_mov_b32_dpp v23, v22 row_bcast:31 row_mask:0xc bank_mask:0xf
	v_add_f32_e32 v22, v22, v23
	s_nop 0
	v_readlane_b32 s44, v22, 63
	ds_read_b128 v[22:25], v55 offset:16
	s_waitcnt lgkmcnt(1)
	v_mul_f32_e32 v15, v15, v19
	v_fmac_f32_e32 v15, v14, v18
	v_mul_f32_e32 v14, v17, v21
	v_fmac_f32_e32 v14, v16, v20
	s_waitcnt lgkmcnt(0)
	v_mul_f32_e32 v11, v11, v23
	v_fmac_f32_e32 v11, v10, v22
	v_mul_f32_e32 v10, v13, v25
	v_add_f32_e32 v14, v15, v14
	v_fmac_f32_e32 v10, v12, v24
	v_add_f32_e32 v18, 0, v14
	ds_read_b128 v[14:17], v55 offset:2048
	v_add_f32_e32 v10, v11, v10
	v_add_f32_e32 v18, v18, v10
	ds_read_b128 v[10:13], v55 offset:2064
	s_waitcnt lgkmcnt(1)
	v_mul_f32_e32 v7, v7, v15
	v_fmac_f32_e32 v7, v6, v14
	v_mul_f32_e32 v6, v9, v17
	s_waitcnt lgkmcnt(0)
	v_mul_f32_e32 v3, v3, v11
	v_fmac_f32_e32 v6, v8, v16
	v_fmac_f32_e32 v3, v2, v10
	v_mul_f32_e32 v2, v5, v13
	v_add_f32_e32 v6, v7, v6
	v_fmac_f32_e32 v2, v4, v12
	v_add_f32_e32 v6, v18, v6
	v_add_f32_e32 v2, v3, v2
	v_add_f32_e32 v2, v6, v2
	v_mov_b32_e32 v3, 0
	s_nop 0
	v_add_f32_dpp v2, v2, v2 quad_perm:[1,0,3,2] row_mask:0xf bank_mask:0xf bound_ctrl:1
	s_nop 1
	v_add_f32_dpp v2, v2, v2 quad_perm:[2,3,0,1] row_mask:0xf bank_mask:0xf bound_ctrl:1
	s_nop 1
	v_add_f32_dpp v2, v2, v2 row_half_mirror row_mask:0xf bank_mask:0xf bound_ctrl:1
	s_nop 1
	v_add_f32_dpp v2, v2, v2 row_mirror row_mask:0xf bank_mask:0xf bound_ctrl:1
	s_nop 1
	v_mov_b32_dpp v3, v2 row_bcast:15 row_mask:0xa bank_mask:0xf
	v_add_f32_e32 v2, v2, v3
	v_mov_b32_e32 v3, 0
	s_nop 1
	v_mov_b32_dpp v3, v2 row_bcast:31 row_mask:0xc bank_mask:0xf
	v_add_f32_e32 v2, v2, v3
	s_nop 0
	v_readlane_b32 s45, v2, 63
	s_and_saveexec_b64 s[36:37], vcc
	s_cbranch_execz .LBB0_10
	v_mov_b32_e32 v2, v149
	v_mov_b32_e32 v3, s27
	v_mov_b32_e32 v4, s39
	v_mov_b32_e32 v5, s40
	v_cndmask_b32_e64 v3, v3, v4, s[16:17]
	v_mov_b32_e32 v6, s41
	v_cndmask_b32_e64 v3, v3, v5, s[4:5]
	v_mov_b32_e32 v7, s42
	v_cndmask_b32_e64 v3, v3, v6, s[6:7]
	v_mov_b32_e32 v8, s43
	v_cndmask_b32_e64 v3, v3, v7, s[8:9]
	v_mov_b32_e32 v9, s44
	v_cndmask_b32_e64 v3, v3, v8, s[10:11]
	v_mov_b32_e32 v10, s45
	v_cndmask_b32_e64 v3, v3, v9, s[12:13]
	s_lshl_b64 s[34:35], s[34:35], 5
	v_cndmask_b32_e64 v3, v3, v10, s[14:15]
	s_nop 0
	v_add_f32_e32 v4, v3, v2
	v_lshl_add_u64 v[2:3], v[44:45], 0, s[34:35]
	global_store_dword v[2:3], v4, off
	s_branch .LBB0_10
